# v38 + NSA lazy-rescale diamond: not-taken 'me = m' v_mov removed at 14 sites (join reads m directly; equal on both paths), exact
# speedup vs baseline: 1.0010x; 1.0010x over previous
; template <int MODE>
; __device__ __forceinline__ void nsa_compute(int cur, int buf, int t, int hl, u64 mymask, const bf16x8 (&Qf)[2][2], f32x4 (&O)[4][2], float (&m)[2], float (&l)[2],
;                                             const float (&inv)[2], float* impw, char* lds) {
;     ...
;     for (int r = 0; r < 2; ++r) {
;       float sv[2][4];
; #pragma unroll
;       for (int kk = 0; kk < 2; ++kk)
; #pragma unroll
;         for (int e = 0; e < 4; ++e) {
;           const int off = 32 * s2 + 16 * kk + e;
;           int idx;
;           if (MODE <= 1) { idx = base - 16 * off; idx = idx > 0 ? idx : 0; } else idx = base - off;
;           sv[kk][e] = S[kk][r][e] * (0.125f * LOG2E) + tb[r * TS + idx];
;         }
;       float pv[2][4];
;       if (MODE == 1) {
; #pragma unroll
;         for (int kk = 0; kk < 2; ++kk)
; #pragma unroll
;           for (int e = 0; e < 4; ++e) pv[kk][e] = __builtin_amdgcn_exp2f(sv[kk][e] - m[r]) * inv[r];
; #pragma unroll
;         for (int kk = 0; kk < 2; ++kk) { g1s[kk] += pv[kk][0] + pv[kk][1] + pv[kk][2] + 0.5f * pv[kk][3]; p3s[kk] += 0.5f * pv[kk][3]; }
;       } else {
;         const float mxa = fmaxf(fmaxf(sv[0][0], sv[0][1]), sv[0][2]), mxb = fmaxf(fmaxf(sv[0][3], sv[1][0]), sv[1][1]);
;         float mx = fmaxf(fmaxf(fmaxf(sv[1][2], sv[1][3]), mxa), mxb);
;         if (MODE == 2) mx = selok ? mx : -__builtin_inff();
;         if (__any(mx > m[r] + 8.0f)) {
;           mx = fmaxf(mx, __shfl_xor(mx, 16)); mx = fmaxf(mx, __shfl_xor(mx, 32));
;           const float mn = fmaxf(m[r], mx), al = __builtin_amdgcn_exp2f(m[r] - mn);
;           m[r] = mn; l[r] *= al;
;           if (MODE != 0) {
; #pragma unroll
;             for (int df = 0; df < 4; ++df) O[df][r] *= al;
;           }
;         }
;         const float me = (MODE == 2) ? (selok ? m[r] : __builtin_inff()) : m[r];
;         float ps = 0.f;
; #pragma unroll
;         for (int kk = 0; kk < 2; ++kk)
; #pragma unroll
;           for (int e = 0; e < 4; ++e) { pv[kk][e] = __builtin_amdgcn_exp2f(sv[kk][e] - me); ps += pv[kk][e]; }
;         l[r] += ps;
;       }
;       if (MODE != 0) {
;         const unsigned w0 = pk2(pv[0][0], pv[0][1]), w1 = pk2(pv[0][2], pv[0][3]), w2 = pk2(pv[1][0], pv[1][1]), w3 = pk2(pv[1][2], pv[1][3]);
;         u32x4 pw; pw.x = w0; pw.y = w1; pw.z = w2; pw.w = w3;
;         Pf[r] = __builtin_bit_cast(bf16x8, pw);
;       }
;     }
.LBB0_363:
.LBB0_364:
	v_sub_f32_e32 v85, v94, v192
	v_exp_f32_e32 v85, v85
	v_sub_f32_e32 v86, v86, v192
	v_exp_f32_e32 v86, v86
	v_sub_f32_e32 v87, v87, v192
	v_exp_f32_e32 v87, v87
	v_sub_f32_e32 v84, v84, v192
	v_exp_f32_e32 v84, v84
	v_add_f32_e32 v89, v86, v85
	v_add_f32_e32 v89, v87, v89
	v_sub_f32_e32 v81, v81, v192
	v_add_f32_e32 v94, v84, v89
	v_exp_f32_e32 v89, v81
	v_sub_f32_e32 v80, v80, v192
	v_add_f32_e32 v81, v89, v94
	v_exp_f32_e32 v94, v80
	s_nop 0
	v_add_f32_e32 v80, v94, v81
	v_sub_f32_e32 v81, v83, v192
	v_exp_f32_e32 v95, v81
	v_sub_f32_e32 v81, v82, v192
	v_exp_f32_e32 v88, v81
	v_add_f32_e32 v80, v95, v80
	v_add_f32_e32 v80, v88, v80
	v_add_f32_e32 v190, v190, v80
	s_waitcnt lgkmcnt(3)
	v_fmamk_f32 v81, v76, 0x3e38aa3b, v173
	v_fmamk_f32 v80, v77, 0x3e38aa3b, v172
	s_waitcnt lgkmcnt(2)
	v_fmamk_f32 v78, v78, 0x3e38aa3b, v175
	v_fmamk_f32 v82, v79, 0x3e38aa3b, v174
	s_waitcnt lgkmcnt(1)
	v_fmamk_f32 v77, v72, 0x3e38aa3b, v195
	v_fmamk_f32 v76, v73, 0x3e38aa3b, v194
	s_waitcnt lgkmcnt(0)
	v_fmamk_f32 v73, v74, 0x3e38aa3b, v199
	v_fmamk_f32 v72, v75, 0x3e38aa3b, v198
	v_max3_f32 v74, v81, v80, v78
	v_max3_f32 v75, v82, v77, v76
	v_max_f32_e32 v79, v73, v72
	v_max3_f32 v74, v79, v74, v75
	v_add_f32_e32 v75, 0x41000000, v193
	v_cmp_gt_f32_e32 vcc, v74, v75
	s_cbranch_vccz .LBB0_366
	ds_bpermute_b32 v75, v233, v74
	v_max_f32_e32 v74, v74, v74
	s_waitcnt lgkmcnt(0)
	v_max_f32_e32 v75, v75, v75
	v_max_f32_e32 v74, v74, v75
	ds_bpermute_b32 v75, v234, v74
	s_waitcnt lgkmcnt(0)
	v_max3_f32 v74, v193, v74, v75
	v_sub_f32_e32 v75, v193, v74
	v_exp_f32_e32 v96, v75
	v_mov_b32_e32 v193, v74
	v_mul_f32_e32 v191, v191, v96
	v_pk_mul_f32 v[106:107], v[106:107], v[96:97] op_sel_hi:[1,0]
	v_pk_mul_f32 v[104:105], v[104:105], v[96:97] op_sel_hi:[1,0]
	v_pk_mul_f32 v[110:111], v[110:111], v[96:97] op_sel_hi:[1,0]
	v_pk_mul_f32 v[108:109], v[108:109], v[96:97] op_sel_hi:[1,0]
	v_pk_mul_f32 v[114:115], v[114:115], v[96:97] op_sel_hi:[1,0]
	v_pk_mul_f32 v[112:113], v[112:113], v[96:97] op_sel_hi:[1,0]
	v_pk_mul_f32 v[122:123], v[122:123], v[96:97] op_sel_hi:[1,0]
	v_pk_mul_f32 v[120:121], v[120:121], v[96:97] op_sel_hi:[1,0]
	s_branch .LBB0_367
.LBB0_366:
.LBB0_367:
	v_sub_f32_e32 v75, v81, v193
	v_exp_f32_e32 v75, v75
	v_sub_f32_e32 v80, v80, v193
	v_exp_f32_e32 v80, v80
	v_sub_f32_e32 v78, v78, v193
	v_exp_f32_e32 v78, v78
	v_sub_f32_e32 v81, v82, v193
	v_exp_f32_e32 v81, v81
	v_sub_f32_e32 v77, v77, v193
	v_exp_f32_e32 v77, v77
	v_sub_f32_e32 v76, v76, v193
	v_add_f32_e32 v79, v80, v75
	v_exp_f32_e32 v76, v76
	v_sub_f32_e32 v73, v73, v193
	v_add_f32_e32 v79, v78, v79
	v_exp_f32_e32 v73, v73
	v_sub_f32_e32 v72, v72, v193
	v_add_f32_e32 v79, v81, v79
	v_exp_f32_e32 v72, v72
	v_add_f32_e32 v79, v77, v79
	v_add_f32_e32 v79, v76, v79
	v_add_f32_e32 v79, v73, v79
	s_lshl_b32 s17, s46, 9
	v_add_f32_e32 v74, v72, v79
	v_cvt_pk_bf16_f32 v149, v73, v72
	v_mul_u32_u24_e32 v72, 0x44, v92
	s_add_i32 s43, s64, s17
	v_lshlrev_b32_e32 v72, 1, v72
	v_lshlrev_b32_e32 v73, 1, v93
	v_cvt_pk_bf16_f32 v146, v75, v80
	v_add3_u32 v80, s43, v72, v73
	v_add_u32_e32 v137, 0x4000, v80
	v_add_u32_e32 v138, 0x4800, v80
	v_add_f32_e32 v191, v191, v74
	v_cvt_pk_bf16_f32 v147, v78, v81
	v_cvt_pk_bf16_f32 v148, v77, v76
	ds_read2_b64 v[72:75], v137 offset1:4
	ds_read2_b64 v[76:79], v138 offset0:16 offset1:20
	v_add_u32_e32 v139, 0x5000, v80
	v_add_u32_e32 v140, 0x5800, v80
	ds_read2_b64 v[150:153], v139 offset0:32 offset1:36
	ds_read2_b64 v[154:157], v140 offset0:48 offset1:52
	v_cvt_pk_bf16_f32 v142, v85, v86
	v_cvt_pk_bf16_f32 v143, v87, v84
	v_cvt_pk_bf16_f32 v144, v89, v94
	v_cvt_pk_bf16_f32 v145, v95, v88
	s_setprio 1
	s_waitcnt lgkmcnt(3)
	v_mfma_f32_16x16x32_bf16 v[84:87], v[72:75], v[142:145], v[116:119]
	v_mfma_f32_16x16x32_bf16 v[96:99], v[72:75], v[146:149], v[104:107]
	s_waitcnt lgkmcnt(2)
	v_mfma_f32_16x16x32_bf16 v[80:83], v[76:79], v[142:145], v[124:127]
	v_mfma_f32_16x16x32_bf16 v[92:95], v[76:79], v[146:149], v[108:111]
	s_waitcnt lgkmcnt(1)
	v_mfma_f32_16x16x32_bf16 v[76:79], v[150:153], v[142:145], v[128:131]
	v_mfma_f32_16x16x32_bf16 v[108:111], v[150:153], v[146:149], v[112:115]
	s_waitcnt lgkmcnt(0)
	v_mfma_f32_16x16x32_bf16 v[72:75], v[154:157], v[142:145], v[132:135]
	v_mfma_f32_16x16x32_bf16 v[104:107], v[154:157], v[146:149], v[120:123]
	s_setprio 0
	v_add_u32_e32 v88, v91, v90
	v_add_u32_e32 v100, v100, v90
	ds_read_b128 v[112:115], v88 offset:4096
	ds_read_b128 v[116:119], v88 offset:6144
	ds_read_b128 v[88:91], v100 offset:4096
	ds_read_b128 v[120:123], v100 offset:6144
	v_add_u32_e32 v251, 0xa00, v136
	ds_read2_b32 v[168:169], v136 offset0:31 offset1:32
	ds_read2_b32 v[170:171], v136 offset0:29 offset1:30
	ds_read2_b32 v[172:173], v136 offset0:15 offset1:16
	ds_read2_b32 v[174:175], v136 offset0:13 offset1:14
	ds_read2_b32 v[198:199], v251 offset0:31 offset1:32
	ds_read2_b32 v[200:201], v251 offset0:29 offset1:30
	ds_read2_b32 v[202:203], v251 offset0:15 offset1:16
	ds_read2_b32 v[204:205], v251 offset0:13 offset1:14
	s_setprio 1
	s_waitcnt lgkmcnt(11)
	v_mfma_f32_16x16x32_bf16 v[100:103], v[112:115], v[0:3], 0
	v_mfma_f32_16x16x32_bf16 v[112:115], v[112:115], v[8:11], 0
	s_waitcnt lgkmcnt(10)
	v_mfma_f32_16x16x32_bf16 v[124:127], v[116:119], v[0:3], 0
	v_mfma_f32_16x16x32_bf16 v[116:119], v[116:119], v[8:11], 0
	s_waitcnt lgkmcnt(9)
	v_mfma_f32_16x16x32_bf16 v[128:131], v[88:91], v[4:7], v[100:103]
	v_mfma_f32_16x16x32_bf16 v[100:103], v[88:91], v[12:15], v[112:115]
	s_waitcnt lgkmcnt(8)
	v_mfma_f32_16x16x32_bf16 v[88:91], v[120:123], v[12:15], v[116:119]
	v_mfma_f32_16x16x32_bf16 v[124:127], v[120:123], v[4:7], v[124:127]
	s_setprio 0
	s_nop 0
	s_waitcnt lgkmcnt(7)
	s_nop 0
	v_fmamk_f32 v123, v128, 0x3e38aa3b, v169
	v_fmamk_f32 v118, v129, 0x3e38aa3b, v168
	s_waitcnt lgkmcnt(6)
	v_fmamk_f32 v122, v130, 0x3e38aa3b, v171
	v_fmamk_f32 v116, v131, 0x3e38aa3b, v170
	s_waitcnt lgkmcnt(5)
	v_fmamk_f32 v119, v124, 0x3e38aa3b, v173
	v_fmamk_f32 v114, v125, 0x3e38aa3b, v172
	s_waitcnt lgkmcnt(4)
	v_fmamk_f32 v113, v126, 0x3e38aa3b, v175
	v_fmamk_f32 v112, v127, 0x3e38aa3b, v174
	v_max3_f32 v115, v123, v118, v122
	v_max3_f32 v117, v116, v119, v114
	v_max_f32_e32 v120, v113, v112
	v_max3_f32 v115, v120, v115, v117
	v_add_f32_e32 v117, 0x41000000, v192
	v_cmp_gt_f32_e32 vcc, v115, v117
	s_cbranch_vccz .LBB0_369
; template <int MODE>
; __device__ __forceinline__ void nsa_compute(int cur, int buf, int t, int hl, u64 mymask, const bf16x8 (&Qf)[2][2], f32x4 (&O)[4][2], float (&m)[2], float (&l)[2],
;                                             const float (&inv)[2], float* impw, char* lds) {
;     ...
;         const float mxa = fmaxf(fmaxf(sv[0][0], sv[0][1]), sv[0][2]), mxb = fmaxf(fmaxf(sv[0][3], sv[1][0]), sv[1][1]);
;         float mx = fmaxf(fmaxf(fmaxf(sv[1][2], sv[1][3]), mxa), mxb);
;         if (MODE == 2) mx = selok ? mx : -__builtin_inff();
;         if (__any(mx > m[r] + 8.0f)) {
;           mx = fmaxf(mx, __shfl_xor(mx, 16)); mx = fmaxf(mx, __shfl_xor(mx, 32));
;           const float mn = fmaxf(m[r], mx), al = __builtin_amdgcn_exp2f(m[r] - mn);
;           m[r] = mn; l[r] *= al;
;           if (MODE != 0) {
; #pragma unroll
;             for (int df = 0; df < 4; ++df) O[df][r] *= al;
;           }
;         }
;         const float me = (MODE == 2) ? (selok ? m[r] : __builtin_inff()) : m[r];
;         float ps = 0.f;
; #pragma unroll
;         for (int kk = 0; kk < 2; ++kk)
; #pragma unroll
;           for (int e = 0; e < 4; ++e) { pv[kk][e] = __builtin_amdgcn_exp2f(sv[kk][e] - me); ps += pv[kk][e]; }
;         l[r] += ps;
	ds_bpermute_b32 v117, v233, v115
	v_max_f32_e32 v115, v115, v115
	v_mov_b32_e32 v121, v193
	s_waitcnt lgkmcnt(0)
	v_max_f32_e32 v117, v117, v117
	v_max_f32_e32 v115, v115, v117
	ds_bpermute_b32 v117, v234, v115
	s_waitcnt lgkmcnt(0)
	v_max3_f32 v120, v192, v115, v117
	v_sub_f32_e32 v115, v192, v120
	v_exp_f32_e32 v124, v115
	v_mov_b64_e32 v[192:193], v[120:121]
	v_mul_f32_e32 v190, v190, v124
	v_pk_mul_f32 v[86:87], v[86:87], v[124:125] op_sel_hi:[1,0]
	v_pk_mul_f32 v[84:85], v[84:85], v[124:125] op_sel_hi:[1,0]
	v_pk_mul_f32 v[82:83], v[82:83], v[124:125] op_sel_hi:[1,0]
	v_pk_mul_f32 v[80:81], v[80:81], v[124:125] op_sel_hi:[1,0]
	v_pk_mul_f32 v[78:79], v[78:79], v[124:125] op_sel_hi:[1,0]
	v_pk_mul_f32 v[76:77], v[76:77], v[124:125] op_sel_hi:[1,0]
	v_pk_mul_f32 v[74:75], v[74:75], v[124:125] op_sel_hi:[1,0]
	v_pk_mul_f32 v[72:73], v[72:73], v[124:125] op_sel_hi:[1,0]
	s_branch .LBB0_370
.LBB0_369:
.LBB0_370:
	v_sub_f32_e32 v115, v123, v192
	v_exp_f32_e32 v115, v115
	v_sub_f32_e32 v117, v118, v192
	v_exp_f32_e32 v117, v117
	v_sub_f32_e32 v118, v122, v192
	v_exp_f32_e32 v118, v118
	v_sub_f32_e32 v116, v116, v192
	v_exp_f32_e32 v116, v116
	v_sub_f32_e32 v119, v119, v192
	v_exp_f32_e32 v119, v119
	v_sub_f32_e32 v114, v114, v192
	v_add_f32_e32 v121, v117, v115
	v_exp_f32_e32 v114, v114
	v_add_f32_e32 v121, v118, v121
	v_add_f32_e32 v121, v116, v121
	v_add_f32_e32 v121, v119, v121
	v_sub_f32_e32 v113, v113, v192
	v_add_f32_e32 v122, v114, v121
	v_exp_f32_e32 v121, v113
	v_sub_f32_e32 v112, v112, v192
	v_exp_f32_e32 v120, v112
	v_add_f32_e32 v113, v121, v122
	v_add_f32_e32 v112, v120, v113
	v_add_f32_e32 v190, v190, v112
	s_waitcnt lgkmcnt(3)
	v_fmamk_f32 v113, v100, 0x3e38aa3b, v199
	v_fmamk_f32 v112, v101, 0x3e38aa3b, v198
	s_waitcnt lgkmcnt(2)
	v_fmamk_f32 v101, v102, 0x3e38aa3b, v201
	v_fmamk_f32 v100, v103, 0x3e38aa3b, v200
	s_waitcnt lgkmcnt(1)
	v_fmamk_f32 v103, v88, 0x3e38aa3b, v203
	v_fmamk_f32 v102, v89, 0x3e38aa3b, v202
	s_waitcnt lgkmcnt(0)
	v_fmamk_f32 v89, v90, 0x3e38aa3b, v205
	v_fmamk_f32 v88, v91, 0x3e38aa3b, v204
	v_max3_f32 v90, v113, v112, v101
	v_max3_f32 v91, v100, v103, v102
	v_max_f32_e32 v122, v89, v88
	v_max3_f32 v90, v122, v90, v91
	v_add_f32_e32 v91, 0x41000000, v193
	v_cmp_gt_f32_e32 vcc, v90, v91
	s_cbranch_vccz .LBB0_372
	ds_bpermute_b32 v91, v233, v90
	v_max_f32_e32 v90, v90, v90
	s_waitcnt lgkmcnt(0)
	v_max_f32_e32 v91, v91, v91
	v_max_f32_e32 v90, v90, v91
	ds_bpermute_b32 v91, v234, v90
	s_waitcnt lgkmcnt(0)
	v_max3_f32 v90, v193, v90, v91
	v_sub_f32_e32 v91, v193, v90
	v_exp_f32_e32 v122, v91
	v_mov_b32_e32 v193, v90
	v_mul_f32_e32 v191, v191, v122
	v_pk_mul_f32 v[98:99], v[98:99], v[122:123] op_sel_hi:[1,0]
	v_pk_mul_f32 v[96:97], v[96:97], v[122:123] op_sel_hi:[1,0]
	v_pk_mul_f32 v[94:95], v[94:95], v[122:123] op_sel_hi:[1,0]
	v_pk_mul_f32 v[92:93], v[92:93], v[122:123] op_sel_hi:[1,0]
	v_pk_mul_f32 v[110:111], v[110:111], v[122:123] op_sel_hi:[1,0]
	v_pk_mul_f32 v[108:109], v[108:109], v[122:123] op_sel_hi:[1,0]
	v_pk_mul_f32 v[106:107], v[106:107], v[122:123] op_sel_hi:[1,0]
	v_pk_mul_f32 v[104:105], v[104:105], v[122:123] op_sel_hi:[1,0]
	v_mov_b64_e32 v[194:195], v[190:191]
	s_branch .LBB0_373

; __device__ __forceinline__ void kv_lwrite(const KVRegs& r, char* lds, int buf) {
;   const int tid = TIDX, row = tid >> 3, cq = tid & 7;
; template <int MODE>
; __device__ __forceinline__ void nsa_compute(int cur, int buf, int t, int hl, u64 mymask, const bf16x8 (&Qf)[2][2], f32x4 (&O)[4][2], float (&m)[2], float (&l)[2],
;                                             const float (&inv)[2], float* impw, char* lds) {
;     ...
;         const float mxa = fmaxf(fmaxf(sv[0][0], sv[0][1]), sv[0][2]), mxb = fmaxf(fmaxf(sv[0][3], sv[1][0]), sv[1][1]);
;         float mx = fmaxf(fmaxf(fmaxf(sv[1][2], sv[1][3]), mxa), mxb);
;         if (MODE == 2) mx = selok ? mx : -__builtin_inff();
;         if (__any(mx > m[r] + 8.0f)) {
;           mx = fmaxf(mx, __shfl_xor(mx, 16)); mx = fmaxf(mx, __shfl_xor(mx, 32));
;           const float mn = fmaxf(m[r], mx), al = __builtin_amdgcn_exp2f(m[r] - mn);
;           m[r] = mn; l[r] *= al;
;           if (MODE != 0) {
; #pragma unroll
;             for (int df = 0; df < 4; ++df) O[df][r] *= al;
;           }
;         }
;         const float me = (MODE == 2) ? (selok ? m[r] : __builtin_inff()) : m[r];
;         float ps = 0.f;
; #pragma unroll
;         for (int kk = 0; kk < 2; ++kk)
; #pragma unroll
;           for (int e = 0; e < 4; ++e) { pv[kk][e] = __builtin_amdgcn_exp2f(sv[kk][e] - me); ps += pv[kk][e]; }
;         l[r] += ps;
;       }
;       if (MODE != 0) {
;         const unsigned w0 = pk2(pv[0][0], pv[0][1]), w1 = pk2(pv[0][2], pv[0][3]), w2 = pk2(pv[1][0], pv[1][1]), w3 = pk2(pv[1][2], pv[1][3]);
;         u32x4 pw; pw.x = w0; pw.y = w1; pw.z = w2; pw.w = w3;
;         Pf[r] = __builtin_bit_cast(bf16x8, pw);
;       }
;     }
;     if (MODE != 0) {
;       bf16x8 vfr[4];
; #pragma unroll
;       for (int df = 0; df < 4; ++df) {
;         const bf16x4 va = *(const bf16x4*)(vt + (df * 16 + fr) * 68 + 32 * s2 + 4 * fq);
;         const bf16x4 vb = *(const bf16x4*)(vt + (df * 16 + fr) * 68 + 32 * s2 + 16 + 4 * fq);
;         bf16x8 vf; vf[0] = va[0]; vf[1] = va[1]; vf[2] = va[2]; vf[3] = va[3]; vf[4] = vb[0]; vf[5] = vb[1]; vf[6] = vb[2]; vf[7] = vb[3];
;         vfr[df] = vf;
;       }
;       __builtin_amdgcn_s_setprio(1);
; #pragma unroll
;       for (int df = 0; df < 4; ++df)
; #pragma unroll
;         for (int r = 0; r < 2; ++r) O[df][r] = mfma16(vfr[df], Pf[r], O[df][r]);
;       __builtin_amdgcn_s_setprio(0);
;     }
.LBB0_387:
.LBB0_388:
	v_sub_f32_e32 v147, v160, v192
	v_exp_f32_e32 v147, v147
	v_sub_f32_e32 v149, v150, v192
	v_exp_f32_e32 v149, v149
	v_sub_f32_e32 v150, v159, v192
	v_exp_f32_e32 v150, v150
	v_sub_f32_e32 v148, v148, v192
	v_exp_f32_e32 v148, v148
	v_sub_f32_e32 v151, v151, v192
	v_exp_f32_e32 v151, v151
	v_sub_f32_e32 v146, v146, v192
	v_add_f32_e32 v153, v149, v147
	v_exp_f32_e32 v146, v146
	v_add_f32_e32 v153, v150, v153
	v_add_f32_e32 v153, v148, v153
	v_add_f32_e32 v153, v151, v153
	v_sub_f32_e32 v145, v145, v192
	v_add_f32_e32 v159, v146, v153
	v_exp_f32_e32 v153, v145
	v_sub_f32_e32 v144, v144, v192
	v_exp_f32_e32 v152, v144
	v_add_f32_e32 v145, v153, v159
	v_add_f32_e32 v144, v152, v145
	v_add_f32_e32 v196, v196, v144
	s_waitcnt lgkmcnt(3)
	v_fmamk_f32 v145, v140, 0x3e38aa3b, v211
	v_fmamk_f32 v144, v141, 0x3e38aa3b, v210
	s_waitcnt lgkmcnt(2)
	v_fmamk_f32 v141, v142, 0x3e38aa3b, v237
	v_fmamk_f32 v140, v143, 0x3e38aa3b, v236
	s_waitcnt lgkmcnt(1)
	v_fmamk_f32 v143, v136, 0x3e38aa3b, v239
	v_fmamk_f32 v142, v137, 0x3e38aa3b, v238
	s_waitcnt lgkmcnt(0)
	v_fmamk_f32 v137, v138, 0x3e38aa3b, v241
	v_fmamk_f32 v136, v139, 0x3e38aa3b, v240
	v_max3_f32 v138, v145, v144, v141
	v_max3_f32 v139, v140, v143, v142
	v_max_f32_e32 v154, v137, v136
	v_max3_f32 v138, v154, v138, v139
	v_add_f32_e32 v139, 0x41000000, v193
	v_cmp_gt_f32_e32 vcc, v138, v139
	s_cbranch_vccz .LBB0_390
	ds_bpermute_b32 v139, v233, v138
	v_max_f32_e32 v138, v138, v138
	s_waitcnt lgkmcnt(0)
	v_max_f32_e32 v139, v139, v139
	v_max_f32_e32 v138, v138, v139
	ds_bpermute_b32 v139, v234, v138
	s_waitcnt lgkmcnt(0)
	v_max3_f32 v138, v193, v138, v139
	v_sub_f32_e32 v139, v193, v138
	v_exp_f32_e32 v154, v139
	v_mov_b32_e32 v193, v138
	v_mul_f32_e32 v197, v197, v154
	v_pk_mul_f32 v[134:135], v[134:135], v[154:155] op_sel_hi:[1,0]
	v_pk_mul_f32 v[132:133], v[132:133], v[154:155] op_sel_hi:[1,0]
	v_pk_mul_f32 v[130:131], v[130:131], v[154:155] op_sel_hi:[1,0]
	v_pk_mul_f32 v[128:129], v[128:129], v[154:155] op_sel_hi:[1,0]
	v_pk_mul_f32 v[126:127], v[126:127], v[154:155] op_sel_hi:[1,0]
	v_pk_mul_f32 v[124:125], v[124:125], v[154:155] op_sel_hi:[1,0]
	v_pk_mul_f32 v[122:123], v[122:123], v[154:155] op_sel_hi:[1,0]
	v_pk_mul_f32 v[120:121], v[120:121], v[154:155] op_sel_hi:[1,0]
	s_branch .LBB0_391
.LBB0_390:
.LBB0_391:
	v_sub_f32_e32 v139, v145, v193
	v_exp_f32_e32 v168, v139
	v_sub_f32_e32 v139, v144, v193
	v_exp_f32_e32 v169, v139
	v_sub_f32_e32 v139, v141, v193
	v_exp_f32_e32 v170, v139
	v_sub_f32_e32 v139, v140, v193
	v_exp_f32_e32 v171, v139
	v_sub_f32_e32 v139, v143, v193
	v_cvt_pk_bf16_f32 v164, v147, v149
	v_cvt_pk_bf16_f32 v165, v150, v148
	v_cvt_pk_bf16_f32 v166, v151, v146
	v_cvt_pk_bf16_f32 v167, v153, v152
	v_exp_f32_e32 v172, v139
	v_sub_f32_e32 v139, v142, v193
	ds_read2_b64 v[140:143], v155 offset0:8 offset1:12
	ds_read2_b64 v[144:147], v156 offset0:24 offset1:28
	ds_read2_b64 v[148:151], v157 offset0:40 offset1:44
	ds_read2_b64 v[152:155], v158 offset0:56 offset1:60
	v_sub_f32_e32 v137, v137, v193
	v_sub_f32_e32 v136, v136, v193
	v_exp_f32_e32 v173, v139
	v_exp_f32_e32 v174, v137
	v_exp_f32_e32 v175, v136
	v_cvt_pk_bf16_f32 v198, v168, v169
	v_cvt_pk_bf16_f32 v199, v170, v171
	v_cvt_pk_bf16_f32 v200, v172, v173
	v_cvt_pk_bf16_f32 v201, v174, v175
	s_setprio 1
	s_waitcnt lgkmcnt(3)
	v_mfma_f32_16x16x32_bf16 v[136:139], v[140:143], v[164:167], v[116:119]
	v_mfma_f32_16x16x32_bf16 v[140:143], v[140:143], v[198:201], v[132:135]
	s_waitcnt lgkmcnt(2)
	v_mfma_f32_16x16x32_bf16 v[156:159], v[144:147], v[164:167], v[112:115]
	v_mfma_f32_16x16x32_bf16 v[144:147], v[144:147], v[198:201], v[128:131]
	s_waitcnt lgkmcnt(1)
	v_mfma_f32_16x16x32_bf16 v[160:163], v[148:151], v[164:167], v[108:111]
	v_mfma_f32_16x16x32_bf16 v[148:151], v[148:151], v[198:201], v[124:127]
	s_waitcnt lgkmcnt(0)
	v_mfma_f32_16x16x32_bf16 v[164:167], v[152:155], v[164:167], v[104:107]
	v_mfma_f32_16x16x32_bf16 v[152:155], v[152:155], v[198:201], v[120:123]
	s_setprio 0
	s_cmp_lt_i32 s42, 0
	s_cbranch_scc1 .LBB0_393
	v_mov_b32 v104, v179
	s_nop 0
	v_ashrrev_i32_e32 v105, 3, v104
	v_xor_b32_e32 v107, v105, v104
	v_lshlrev_b32_e32 v104, 3, v104
	v_lshlrev_b32_e32 v107, 4, v107
	v_and_b32_e32 v104, 56, v104
	v_lshlrev_b32_e32 v106, 7, v105
	v_and_b32_e32 v107, 0x70, v107
	v_mul_u32_u24_e32 v104, 0x88, v104
	v_lshlrev_b32_e32 v105, 1, v105
	v_add3_u32 v106, s64, v106, v107
	v_add3_u32 v104, s43, v104, v105
	s_waitcnt vmcnt(1)
	ds_write_b128 v106, v[64:67]
	s_waitcnt vmcnt(0)
	ds_write_b16 v104, v68 offset:16384
	ds_write_b16_d16_hi v104, v68 offset:16520
	ds_write_b16 v104, v69 offset:16656
	ds_write_b16_d16_hi v104, v69 offset:16792
	ds_write_b16 v104, v70 offset:16928
	ds_write_b16_d16_hi v104, v70 offset:17064
	ds_write_b16 v104, v71 offset:17200
	ds_write_b16_d16_hi v104, v71 offset:17336

; __device__ __forceinline__ void kv_lwrite(const KVRegs& r, char* lds, int buf) {
;   const int tid = TIDX, row = tid >> 3, cq = tid & 7;
; template <int MODE>
; __device__ __forceinline__ void nsa_compute(int cur, int buf, int t, int hl, u64 mymask, const bf16x8 (&Qf)[2][2], f32x4 (&O)[4][2], float (&m)[2], float (&l)[2],
;                                             const float (&inv)[2], float* impw, char* lds) {
;     ...
;         const float mxa = fmaxf(fmaxf(sv[0][0], sv[0][1]), sv[0][2]), mxb = fmaxf(fmaxf(sv[0][3], sv[1][0]), sv[1][1]);
;         float mx = fmaxf(fmaxf(fmaxf(sv[1][2], sv[1][3]), mxa), mxb);
;         if (MODE == 2) mx = selok ? mx : -__builtin_inff();
;         if (__any(mx > m[r] + 8.0f)) {
;           mx = fmaxf(mx, __shfl_xor(mx, 16)); mx = fmaxf(mx, __shfl_xor(mx, 32));
;           const float mn = fmaxf(m[r], mx), al = __builtin_amdgcn_exp2f(m[r] - mn);
;           m[r] = mn; l[r] *= al;
;           if (MODE != 0) {
; #pragma unroll
;             for (int df = 0; df < 4; ++df) O[df][r] *= al;
;           }
;         }
;         const float me = (MODE == 2) ? (selok ? m[r] : __builtin_inff()) : m[r];
;         float ps = 0.f;
; #pragma unroll
;         for (int kk = 0; kk < 2; ++kk)
; #pragma unroll
;           for (int e = 0; e < 4; ++e) { pv[kk][e] = __builtin_amdgcn_exp2f(sv[kk][e] - me); ps += pv[kk][e]; }
;         l[r] += ps;
;       }
;       if (MODE != 0) {
;         const unsigned w0 = pk2(pv[0][0], pv[0][1]), w1 = pk2(pv[0][2], pv[0][3]), w2 = pk2(pv[1][0], pv[1][1]), w3 = pk2(pv[1][2], pv[1][3]);
;         u32x4 pw; pw.x = w0; pw.y = w1; pw.z = w2; pw.w = w3;
;         Pf[r] = __builtin_bit_cast(bf16x8, pw);
;       }
;     }
;     if (MODE != 0) {
;       bf16x8 vfr[4];
; #pragma unroll
;       for (int df = 0; df < 4; ++df) {
;         const bf16x4 va = *(const bf16x4*)(vt + (df * 16 + fr) * 68 + 32 * s2 + 4 * fq);
;         const bf16x4 vb = *(const bf16x4*)(vt + (df * 16 + fr) * 68 + 32 * s2 + 16 + 4 * fq);
;         bf16x8 vf; vf[0] = va[0]; vf[1] = va[1]; vf[2] = va[2]; vf[3] = va[3]; vf[4] = vb[0]; vf[5] = vb[1]; vf[6] = vb[2]; vf[7] = vb[3];
;         vfr[df] = vf;
;       }
;       __builtin_amdgcn_s_setprio(1);
; #pragma unroll
;       for (int df = 0; df < 4; ++df)
; #pragma unroll
;         for (int r = 0; r < 2; ++r) O[df][r] = mfma16(vfr[df], Pf[r], O[df][r]);
;       __builtin_amdgcn_s_setprio(0);
;     }
.LBB0_404:
.LBB0_405:
	v_sub_f32_e32 v201, v241, v192
	v_exp_f32_e32 v201, v201
	v_sub_f32_e32 v203, v204, v192
	v_exp_f32_e32 v203, v203
	v_sub_f32_e32 v204, v240, v192
	v_exp_f32_e32 v204, v204
	v_sub_f32_e32 v202, v202, v192
	v_exp_f32_e32 v202, v202
	v_sub_f32_e32 v205, v205, v192
	v_exp_f32_e32 v205, v205
	v_sub_f32_e32 v200, v200, v192
	v_add_f32_e32 v207, v203, v201
	v_exp_f32_e32 v200, v200
	v_add_f32_e32 v207, v204, v207
	v_add_f32_e32 v207, v202, v207
	v_add_f32_e32 v207, v205, v207
	v_sub_f32_e32 v199, v199, v192
	v_add_f32_e32 v208, v200, v207
	v_exp_f32_e32 v207, v199
	v_sub_f32_e32 v198, v198, v192
	v_exp_f32_e32 v206, v198
	v_add_f32_e32 v199, v207, v208
	v_add_f32_e32 v198, v206, v199
	v_add_f32_e32 v190, v190, v198
	v_add_u32_e32 v198, 0xa7c, v176
	ds_read2_b32 v[198:199], v198 offset1:1
	s_waitcnt lgkmcnt(0)
	v_fmamk_f32 v199, v172, 0x3e38aa3b, v199
	v_add_u32_e32 v172, 0xa74, v176
	v_fmac_f32_e32 v198, 0x3e38aa3b, v173
	ds_read2_b32 v[172:173], v172 offset1:1
	s_waitcnt lgkmcnt(0)
	v_fmamk_f32 v173, v174, 0x3e38aa3b, v173
	v_add_u32_e32 v174, 0xa3c, v176
	v_fmac_f32_e32 v172, 0x3e38aa3b, v175
	ds_read2_b32 v[174:175], v174 offset1:1
	s_waitcnt lgkmcnt(0)
	v_fmamk_f32 v240, v116, 0x3e38aa3b, v175
	v_add_u32_e32 v116, 0xa34, v176
	v_fmac_f32_e32 v174, 0x3e38aa3b, v117
	ds_read2_b32 v[116:117], v116 offset1:1
	s_waitcnt lgkmcnt(0)
	v_fmamk_f32 v117, v118, 0x3e38aa3b, v117
	v_fmac_f32_e32 v116, 0x3e38aa3b, v119
	v_max3_f32 v118, v199, v198, v173
	v_max3_f32 v119, v172, v240, v174
	v_max_f32_e32 v175, v117, v116
	v_max3_f32 v118, v175, v118, v119
	v_add_f32_e32 v119, 0x41000000, v193
	v_cmp_gt_f32_e32 vcc, v118, v119
	s_cbranch_vccz .LBB0_407
	ds_bpermute_b32 v119, v233, v118
	v_max_f32_e32 v118, v118, v118
	s_waitcnt lgkmcnt(0)
	v_max_f32_e32 v119, v119, v119
	v_max_f32_e32 v118, v118, v119
	ds_bpermute_b32 v119, v234, v118
	s_waitcnt lgkmcnt(0)
	v_max3_f32 v118, v193, v118, v119
	v_sub_f32_e32 v119, v193, v118
	v_exp_f32_e32 v176, v119
	v_mov_b32_e32 v193, v118
	v_mul_f32_e32 v191, v191, v176
	v_pk_mul_f32 v[126:127], v[126:127], v[176:177] op_sel_hi:[1,0]
	v_pk_mul_f32 v[124:125], v[124:125], v[176:177] op_sel_hi:[1,0]
	v_pk_mul_f32 v[130:131], v[130:131], v[176:177] op_sel_hi:[1,0]
	v_pk_mul_f32 v[128:129], v[128:129], v[176:177] op_sel_hi:[1,0]
	v_pk_mul_f32 v[134:135], v[134:135], v[176:177] op_sel_hi:[1,0]
	v_pk_mul_f32 v[132:133], v[132:133], v[176:177] op_sel_hi:[1,0]
	v_pk_mul_f32 v[170:171], v[170:171], v[176:177] op_sel_hi:[1,0]
	v_pk_mul_f32 v[168:169], v[168:169], v[176:177] op_sel_hi:[1,0]
	s_branch .LBB0_408
.LBB0_407:
.LBB0_408:
	v_sub_f32_e32 v119, v199, v193
	v_exp_f32_e32 v175, v119
	v_sub_f32_e32 v119, v198, v193
	v_exp_f32_e32 v198, v119
	v_sub_f32_e32 v119, v173, v193
	v_exp_f32_e32 v173, v119
	v_sub_f32_e32 v119, v172, v193
	v_cvt_pk_bf16_f32 v208, v201, v203
	v_cvt_pk_bf16_f32 v209, v204, v202
	v_cvt_pk_bf16_f32 v210, v205, v200
	v_exp_f32_e32 v172, v119
	v_sub_f32_e32 v119, v240, v193
	ds_read2_b64 v[202:205], v236 offset0:8 offset1:12
	ds_read2_b64 v[240:243], v237 offset0:24 offset1:28
	ds_read2_b64 v[244:247], v238 offset0:40 offset1:44
	ds_read2_b64 v[236:239], v239 offset0:56 offset1:60
	v_exp_f32_e32 v199, v119
	v_sub_f32_e32 v119, v174, v193
	v_sub_f32_e32 v117, v117, v193
	v_sub_f32_e32 v116, v116, v193
	v_exp_f32_e32 v174, v119
	v_exp_f32_e32 v200, v117
	v_exp_f32_e32 v201, v116
	v_cvt_pk_bf16_f32 v211, v207, v206
	v_cvt_pk_bf16_f32 v248, v175, v198
	v_cvt_pk_bf16_f32 v249, v173, v172
	v_cvt_pk_bf16_f32 v250, v199, v174
	v_cvt_pk_bf16_f32 v251, v200, v201
	s_setprio 1
	s_waitcnt lgkmcnt(3)
	v_mfma_f32_16x16x32_bf16 v[116:119], v[202:205], v[208:211], v[104:107]
	v_mfma_f32_16x16x32_bf16 v[104:107], v[202:205], v[248:251], v[124:127]
	s_waitcnt lgkmcnt(2)
	v_mfma_f32_16x16x32_bf16 v[124:127], v[240:243], v[208:211], v[108:111]
	v_mfma_f32_16x16x32_bf16 v[108:111], v[240:243], v[248:251], v[128:131]
	s_waitcnt lgkmcnt(1)
	v_mfma_f32_16x16x32_bf16 v[128:131], v[244:247], v[208:211], v[112:115]
	v_mfma_f32_16x16x32_bf16 v[112:115], v[244:247], v[248:251], v[132:135]
	s_waitcnt lgkmcnt(0)
	v_mfma_f32_16x16x32_bf16 v[132:135], v[236:239], v[208:211], v[120:123]
	v_mfma_f32_16x16x32_bf16 v[120:123], v[236:239], v[248:251], v[168:171]
	s_setprio 0
	s_cmp_lt_i32 s74, 0
	s_cbranch_scc1 .LBB0_410
	v_mov_b32 v168, v179
	s_nop 0
	v_ashrrev_i32_e32 v169, 3, v168
	v_xor_b32_e32 v171, v169, v168
	v_lshlrev_b32_e32 v168, 3, v168
	v_lshlrev_b32_e32 v171, 4, v171
	v_and_b32_e32 v168, 56, v168
	v_lshlrev_b32_e32 v170, 7, v169
	v_and_b32_e32 v171, 0x70, v171
	v_mul_u32_u24_e32 v168, 0x88, v168
	v_lshlrev_b32_e32 v169, 1, v169
	v_add3_u32 v170, s71, v170, v171
	v_add3_u32 v168, s72, v168, v169
	s_waitcnt vmcnt(1)
	ds_write_b128 v170, v[48:51]
	s_waitcnt vmcnt(0)
	ds_write_b16 v168, v52 offset:16384
	ds_write_b16_d16_hi v168, v52 offset:16520
	ds_write_b16 v168, v53 offset:16656
	ds_write_b16_d16_hi v168, v53 offset:16792
	ds_write_b16 v168, v54 offset:16928
	ds_write_b16_d16_hi v168, v54 offset:17064
	ds_write_b16 v168, v55 offset:17200
	ds_write_b16_d16_hi v168, v55 offset:17336

; template <int MODE>
; __device__ __forceinline__ void nsa_compute(int cur, int buf, int t, int hl, u64 mymask, const bf16x8 (&Qf)[2][2], f32x4 (&O)[4][2], float (&m)[2], float (&l)[2],
;                                             const float (&inv)[2], float* impw, char* lds) {
;     ...
;     for (int r = 0; r < 2; ++r) {
;       float sv[2][4];
; #pragma unroll
;       for (int kk = 0; kk < 2; ++kk)
; #pragma unroll
;         for (int e = 0; e < 4; ++e) {
;           const int off = 32 * s2 + 16 * kk + e;
;           int idx;
;           if (MODE <= 1) { idx = base - 16 * off; idx = idx > 0 ? idx : 0; } else idx = base - off;
;           sv[kk][e] = S[kk][r][e] * (0.125f * LOG2E) + tb[r * TS + idx];
;         }
;       float pv[2][4];
;       if (MODE == 1) {
; #pragma unroll
;         for (int kk = 0; kk < 2; ++kk)
; #pragma unroll
;           for (int e = 0; e < 4; ++e) pv[kk][e] = __builtin_amdgcn_exp2f(sv[kk][e] - m[r]) * inv[r];
; #pragma unroll
;         for (int kk = 0; kk < 2; ++kk) { g1s[kk] += pv[kk][0] + pv[kk][1] + pv[kk][2] + 0.5f * pv[kk][3]; p3s[kk] += 0.5f * pv[kk][3]; }
;       } else {
;         const float mxa = fmaxf(fmaxf(sv[0][0], sv[0][1]), sv[0][2]), mxb = fmaxf(fmaxf(sv[0][3], sv[1][0]), sv[1][1]);
;         float mx = fmaxf(fmaxf(fmaxf(sv[1][2], sv[1][3]), mxa), mxb);
;         if (MODE == 2) mx = selok ? mx : -__builtin_inff();
;         if (__any(mx > m[r] + 8.0f)) {
;           mx = fmaxf(mx, __shfl_xor(mx, 16)); mx = fmaxf(mx, __shfl_xor(mx, 32));
;           const float mn = fmaxf(m[r], mx), al = __builtin_amdgcn_exp2f(m[r] - mn);
;           m[r] = mn; l[r] *= al;
;           if (MODE != 0) {
; #pragma unroll
;             for (int df = 0; df < 4; ++df) O[df][r] *= al;
;           }
;         }
;         const float me = (MODE == 2) ? (selok ? m[r] : __builtin_inff()) : m[r];
;         float ps = 0.f;
; #pragma unroll
;         for (int kk = 0; kk < 2; ++kk)
; #pragma unroll
;           for (int e = 0; e < 4; ++e) { pv[kk][e] = __builtin_amdgcn_exp2f(sv[kk][e] - me); ps += pv[kk][e]; }
;         l[r] += ps;
;       }
;       if (MODE != 0) {
;         const unsigned w0 = pk2(pv[0][0], pv[0][1]), w1 = pk2(pv[0][2], pv[0][3]), w2 = pk2(pv[1][0], pv[1][1]), w3 = pk2(pv[1][2], pv[1][3]);
;         u32x4 pw; pw.x = w0; pw.y = w1; pw.z = w2; pw.w = w3;
;         Pf[r] = __builtin_bit_cast(bf16x8, pw);
;       }
;     }
.LBB0_438:
.LBB0_439:
	v_cndmask_b32_e64 v98, v188, v228, s[36:37]
	v_sub_f32_e32 v85, v87, v98
	v_exp_f32_e32 v85, v85
	v_sub_f32_e32 v86, v86, v98
	v_exp_f32_e32 v86, v86
	v_sub_f32_e32 v83, v83, v98
	v_add_f32_e32 v87, 0, v85
	v_sub_f32_e32 v82, v82, v98
	v_add_f32_e32 v88, v86, v87
	v_exp_f32_e32 v87, v83
	v_sub_f32_e32 v81, v81, v98
	v_exp_f32_e32 v89, v81
	v_sub_f32_e32 v80, v80, v98
	v_add_f32_e32 v83, v87, v88
	v_exp_f32_e32 v88, v82
	v_exp_f32_e32 v96, v80
	v_add_f32_e32 v82, v88, v83
	v_add_f32_e32 v81, v89, v82
	v_add_f32_e32 v80, v96, v81
	v_sub_f32_e32 v81, v97, v98
	v_exp_f32_e32 v97, v81
	v_sub_f32_e32 v81, v84, v98
	v_exp_f32_e32 v84, v81
	v_add_f32_e32 v80, v97, v80
	v_add_f32_e32 v80, v84, v80
	v_add_f32_e32 v190, v190, v80
	s_waitcnt lgkmcnt(3)
	v_fmamk_f32 v81, v76, 0x3e38aa3b, v141
	v_fmamk_f32 v80, v77, 0x3e38aa3b, v140
	s_waitcnt lgkmcnt(2)
	v_fmamk_f32 v78, v78, 0x3e38aa3b, v143
	v_fmamk_f32 v82, v79, 0x3e38aa3b, v142
	s_waitcnt lgkmcnt(1)
	v_fmamk_f32 v77, v72, 0x3e38aa3b, v145
	v_fmamk_f32 v76, v73, 0x3e38aa3b, v144
	s_waitcnt lgkmcnt(0)
	v_fmamk_f32 v73, v74, 0x3e38aa3b, v149
	v_fmamk_f32 v72, v75, 0x3e38aa3b, v148
	v_max3_f32 v74, v81, v80, v78
	v_max3_f32 v75, v82, v77, v76
	v_max_f32_e32 v79, v73, v72
	v_max3_f32 v74, v79, v74, v75
	v_cndmask_b32_e64 v74, v74, v225, s[36:37]
	v_add_f32_e32 v75, 0x41000000, v189
	v_cmp_gt_f32_e32 vcc, v74, v75
	s_cbranch_vccz .LBB0_441
	ds_bpermute_b32 v75, v233, v74
	v_max_f32_e32 v74, v74, v74
	s_waitcnt lgkmcnt(0)
	v_max_f32_e32 v75, v75, v75
	v_max_f32_e32 v74, v74, v75
	ds_bpermute_b32 v75, v234, v74
	s_waitcnt lgkmcnt(0)
	v_max3_f32 v74, v189, v74, v75
	v_sub_f32_e32 v75, v189, v74
	v_exp_f32_e32 v98, v75
	v_mov_b32_e32 v189, v74
	v_mul_f32_e32 v191, v191, v98
	v_pk_mul_f32 v[22:23], v[22:23], v[98:99] op_sel_hi:[1,0]
	v_pk_mul_f32 v[20:21], v[20:21], v[98:99] op_sel_hi:[1,0]
	v_pk_mul_f32 v[30:31], v[30:31], v[98:99] op_sel_hi:[1,0]
	v_pk_mul_f32 v[28:29], v[28:29], v[98:99] op_sel_hi:[1,0]
	v_pk_mul_f32 v[38:39], v[38:39], v[98:99] op_sel_hi:[1,0]
	v_pk_mul_f32 v[36:37], v[36:37], v[98:99] op_sel_hi:[1,0]
	v_pk_mul_f32 v[46:47], v[46:47], v[98:99] op_sel_hi:[1,0]
	v_pk_mul_f32 v[44:45], v[44:45], v[98:99] op_sel_hi:[1,0]
	s_branch .LBB0_442
.LBB0_441:
.LBB0_442:
	v_cndmask_b32_e64 v74, v189, v228, s[36:37]
	v_sub_f32_e32 v75, v81, v74
	v_exp_f32_e32 v75, v75
	v_sub_f32_e32 v80, v80, v74
	v_exp_f32_e32 v80, v80
	v_sub_f32_e32 v78, v78, v74
	v_exp_f32_e32 v78, v78
	v_sub_f32_e32 v81, v82, v74
	v_exp_f32_e32 v81, v81
	v_sub_f32_e32 v77, v77, v74
	v_exp_f32_e32 v77, v77
	v_sub_f32_e32 v76, v76, v74
	v_add_f32_e32 v79, v80, v75
	v_exp_f32_e32 v76, v76
	v_sub_f32_e32 v73, v73, v74
	v_add_f32_e32 v79, v78, v79
	v_exp_f32_e32 v73, v73
	v_sub_f32_e32 v72, v72, v74
	v_add_f32_e32 v79, v81, v79
	v_exp_f32_e32 v72, v72
	v_add_f32_e32 v79, v77, v79
	v_add_f32_e32 v79, v76, v79
	v_add_f32_e32 v79, v73, v79
	s_lshl_b32 s17, s74, 9
	v_add_f32_e32 v74, v72, v79
	v_cvt_pk_bf16_f32 v101, v73, v72
	v_mul_u32_u24_e32 v72, 0x44, v94
	s_add_i32 s71, s63, s17
	v_lshlrev_b32_e32 v72, 1, v72
	v_lshlrev_b32_e32 v73, 1, v95
	v_add3_u32 v72, s71, v72, v73
	v_add_u32_e32 v94, 0x4000, v72
	v_cvt_pk_bf16_f32 v87, v87, v88
	v_cvt_pk_bf16_f32 v88, v89, v96
	v_cvt_pk_bf16_f32 v89, v97, v84
	v_cvt_pk_bf16_f32 v99, v78, v81
	v_cvt_pk_bf16_f32 v100, v77, v76
	ds_read2_b64 v[76:79], v94 offset1:4
	v_add_u32_e32 v95, 0x4800, v72
	v_add_u32_e32 v96, 0x5000, v72
	v_add_u32_e32 v97, 0x5800, v72
	ds_read2_b64 v[102:105], v95 offset0:16 offset1:20
	ds_read2_b64 v[106:109], v96 offset0:32 offset1:36
	ds_read2_b64 v[110:113], v97 offset0:48 offset1:52
	v_cvt_pk_bf16_f32 v86, v85, v86
	v_add_f32_e32 v191, v191, v74
	v_cvt_pk_bf16_f32 v98, v75, v80
	s_setprio 1
	s_waitcnt lgkmcnt(3)
	v_mfma_f32_16x16x32_bf16 v[72:75], v[76:79], v[86:89], v[16:19]
	v_mfma_f32_16x16x32_bf16 v[80:83], v[76:79], v[98:101], v[20:23]
	s_waitcnt lgkmcnt(2)
	v_mfma_f32_16x16x32_bf16 v[24:27], v[102:105], v[86:89], v[24:27]
	v_mfma_f32_16x16x32_bf16 v[76:79], v[102:105], v[98:101], v[28:31]
	s_waitcnt lgkmcnt(1)
	v_mfma_f32_16x16x32_bf16 v[20:23], v[106:109], v[86:89], v[32:35]
	v_mfma_f32_16x16x32_bf16 v[32:35], v[106:109], v[98:101], v[36:39]
	s_waitcnt lgkmcnt(0)
	v_mfma_f32_16x16x32_bf16 v[16:19], v[110:113], v[86:89], v[40:43]
	v_mfma_f32_16x16x32_bf16 v[28:31], v[110:113], v[98:101], v[44:47]
	s_setprio 0
	s_nop 0
	v_add_u32_e32 v40, v92, v91
	v_add_u32_e32 v84, v93, v91
	ds_read_b128 v[36:39], v40 offset:4096
	ds_read_b128 v[40:43], v40 offset:6144
	ds_read_b128 v[44:47], v84 offset:4096
	ds_read_b128 v[84:87], v84 offset:6144
	v_add_u32_e32 v251, 0x8400, v90
	v_add_u32_e32 v250, 0xc500, v90
	ds_read2_b32 v[138:139], v251 offset0:31 offset1:32
	ds_read2_b32 v[140:141], v251 offset0:29 offset1:30
	ds_read2_b32 v[142:143], v251 offset0:15 offset1:16
	ds_read2_b32 v[148:149], v251 offset0:13 offset1:14
	ds_read2_b32 v[150:151], v250 offset0:31 offset1:32
	ds_read2_b32 v[152:153], v250 offset0:29 offset1:30
	ds_read2_b32 v[154:155], v250 offset0:15 offset1:16
	ds_read2_b32 v[156:157], v250 offset0:13 offset1:14
	s_setprio 1
	s_waitcnt lgkmcnt(11)
	v_mfma_f32_16x16x32_bf16 v[98:101], v[36:39], v[0:3], 0
	v_mfma_f32_16x16x32_bf16 v[36:39], v[36:39], v[8:11], 0
	s_waitcnt lgkmcnt(10)
	v_mfma_f32_16x16x32_bf16 v[106:109], v[40:43], v[8:11], 0
	v_mfma_f32_16x16x32_bf16 v[102:105], v[40:43], v[0:3], 0
	s_waitcnt lgkmcnt(9)
	v_mfma_f32_16x16x32_bf16 v[40:43], v[44:47], v[12:15], v[36:39]
	s_waitcnt lgkmcnt(8)
	v_mfma_f32_16x16x32_bf16 v[36:39], v[84:87], v[12:15], v[106:109]
	v_mfma_f32_16x16x32_bf16 v[98:101], v[44:47], v[4:7], v[98:101]
	v_mfma_f32_16x16x32_bf16 v[102:105], v[84:87], v[4:7], v[102:105]
	s_setprio 0
	s_waitcnt lgkmcnt(7)
	s_nop 4
	v_fmamk_f32 v91, v98, 0x3e38aa3b, v139
	v_fmamk_f32 v84, v99, 0x3e38aa3b, v138
	s_waitcnt lgkmcnt(6)
	v_fmamk_f32 v85, v100, 0x3e38aa3b, v141
	v_fmamk_f32 v46, v101, 0x3e38aa3b, v140
	s_waitcnt lgkmcnt(5)
	v_fmamk_f32 v45, v102, 0x3e38aa3b, v143
	v_fmamk_f32 v44, v103, 0x3e38aa3b, v142
	v_max3_f32 v47, v91, v84, v85
	s_waitcnt lgkmcnt(4)
	v_fmamk_f32 v92, v104, 0x3e38aa3b, v149
	v_fmamk_f32 v86, v105, 0x3e38aa3b, v148
	v_max3_f32 v87, v46, v45, v44
	v_max_f32_e32 v88, v92, v86
	v_max3_f32 v47, v88, v47, v87
	v_cndmask_b32_e64 v47, v47, v225, s[36:37]
	v_add_f32_e32 v87, 0x41000000, v188
	v_cmp_gt_f32_e32 vcc, v47, v87
	s_cbranch_vccz .LBB0_444
; template <int MODE>
; __device__ __forceinline__ void nsa_compute(int cur, int buf, int t, int hl, u64 mymask, const bf16x8 (&Qf)[2][2], f32x4 (&O)[4][2], float (&m)[2], float (&l)[2],
;                                             const float (&inv)[2], float* impw, char* lds) {
;     ...
;         const float mxa = fmaxf(fmaxf(sv[0][0], sv[0][1]), sv[0][2]), mxb = fmaxf(fmaxf(sv[0][3], sv[1][0]), sv[1][1]);
;         float mx = fmaxf(fmaxf(fmaxf(sv[1][2], sv[1][3]), mxa), mxb);
;         if (MODE == 2) mx = selok ? mx : -__builtin_inff();
;         if (__any(mx > m[r] + 8.0f)) {
;           mx = fmaxf(mx, __shfl_xor(mx, 16)); mx = fmaxf(mx, __shfl_xor(mx, 32));
;           const float mn = fmaxf(m[r], mx), al = __builtin_amdgcn_exp2f(m[r] - mn);
;           m[r] = mn; l[r] *= al;
;           if (MODE != 0) {
; #pragma unroll
;             for (int df = 0; df < 4; ++df) O[df][r] *= al;
;           }
;         }
;         const float me = (MODE == 2) ? (selok ? m[r] : __builtin_inff()) : m[r];
;         float ps = 0.f;
; #pragma unroll
;         for (int kk = 0; kk < 2; ++kk)
; #pragma unroll
;           for (int e = 0; e < 4; ++e) { pv[kk][e] = __builtin_amdgcn_exp2f(sv[kk][e] - me); ps += pv[kk][e]; }
;         l[r] += ps;
	ds_bpermute_b32 v87, v233, v47
	v_max_f32_e32 v47, v47, v47
	v_mov_b32_e32 v89, v189
	s_waitcnt lgkmcnt(0)
	v_max_f32_e32 v87, v87, v87
	v_max_f32_e32 v47, v47, v87
	ds_bpermute_b32 v87, v234, v47
	s_waitcnt lgkmcnt(0)
	v_max3_f32 v88, v188, v47, v87
	v_sub_f32_e32 v47, v188, v88
	v_exp_f32_e32 v98, v47
	v_mov_b64_e32 v[188:189], v[88:89]
	v_mul_f32_e32 v190, v190, v98
	v_pk_mul_f32 v[74:75], v[74:75], v[98:99] op_sel_hi:[1,0]
	v_pk_mul_f32 v[72:73], v[72:73], v[98:99] op_sel_hi:[1,0]
	v_pk_mul_f32 v[26:27], v[26:27], v[98:99] op_sel_hi:[1,0]
	v_pk_mul_f32 v[24:25], v[24:25], v[98:99] op_sel_hi:[1,0]
	v_pk_mul_f32 v[22:23], v[22:23], v[98:99] op_sel_hi:[1,0]
	v_pk_mul_f32 v[20:21], v[20:21], v[98:99] op_sel_hi:[1,0]
	v_pk_mul_f32 v[18:19], v[18:19], v[98:99] op_sel_hi:[1,0]
	v_pk_mul_f32 v[16:17], v[16:17], v[98:99] op_sel_hi:[1,0]
	s_branch .LBB0_445
.LBB0_444:
.LBB0_445:
	v_cndmask_b32_e64 v93, v188, v228, s[36:37]
	v_sub_f32_e32 v47, v91, v93
	v_exp_f32_e32 v47, v47
	v_sub_f32_e32 v84, v84, v93
	v_exp_f32_e32 v84, v84
	v_sub_f32_e32 v85, v85, v93
	v_exp_f32_e32 v85, v85
	v_sub_f32_e32 v46, v46, v93
	v_exp_f32_e32 v46, v46
	v_add_f32_e32 v87, v84, v47
	v_add_f32_e32 v87, v85, v87
	v_sub_f32_e32 v45, v45, v93
	v_add_f32_e32 v88, v46, v87
	v_exp_f32_e32 v87, v45
	v_sub_f32_e32 v44, v44, v93
	v_add_f32_e32 v45, v87, v88
	v_exp_f32_e32 v88, v44
	s_nop 0
	v_add_f32_e32 v44, v88, v45
	v_sub_f32_e32 v45, v92, v93
	v_exp_f32_e32 v89, v45
	v_sub_f32_e32 v45, v86, v93
	v_exp_f32_e32 v86, v45
	v_add_f32_e32 v44, v89, v44
	v_add_f32_e32 v44, v86, v44
	v_add_f32_e32 v190, v190, v44
	s_waitcnt lgkmcnt(3)
	v_fmamk_f32 v45, v40, 0x3e38aa3b, v151
	v_fmamk_f32 v44, v41, 0x3e38aa3b, v150
	s_waitcnt lgkmcnt(2)
	v_fmamk_f32 v41, v42, 0x3e38aa3b, v153
	v_fmamk_f32 v40, v43, 0x3e38aa3b, v152
	s_waitcnt lgkmcnt(1)
	v_fmamk_f32 v43, v36, 0x3e38aa3b, v155
	v_fmamk_f32 v42, v37, 0x3e38aa3b, v154
	s_waitcnt lgkmcnt(0)
	v_fmamk_f32 v90, v38, 0x3e38aa3b, v157
	v_fmamk_f32 v36, v39, 0x3e38aa3b, v156
	v_max3_f32 v37, v45, v44, v41
	v_max3_f32 v38, v40, v43, v42
	v_max_f32_e32 v39, v90, v36
	v_max3_f32 v37, v39, v37, v38
	v_cndmask_b32_e64 v37, v37, v225, s[36:37]
	v_add_f32_e32 v38, 0x41000000, v189
	v_cmp_gt_f32_e32 vcc, v37, v38
	s_cbranch_vccz .LBB0_447
	ds_bpermute_b32 v38, v233, v37
	v_max_f32_e32 v37, v37, v37
	s_waitcnt lgkmcnt(0)
	v_max_f32_e32 v38, v38, v38
	v_max_f32_e32 v37, v37, v38
	ds_bpermute_b32 v38, v234, v37
	s_waitcnt lgkmcnt(0)
	v_max3_f32 v37, v189, v37, v38
	v_sub_f32_e32 v38, v189, v37
	v_exp_f32_e32 v38, v38
	v_mov_b32_e32 v189, v37
	v_mul_f32_e32 v191, v191, v38
	v_pk_mul_f32 v[82:83], v[82:83], v[38:39] op_sel_hi:[1,0]
	v_pk_mul_f32 v[80:81], v[80:81], v[38:39] op_sel_hi:[1,0]
	v_pk_mul_f32 v[78:79], v[78:79], v[38:39] op_sel_hi:[1,0]
	v_pk_mul_f32 v[76:77], v[76:77], v[38:39] op_sel_hi:[1,0]
	v_pk_mul_f32 v[34:35], v[34:35], v[38:39] op_sel_hi:[1,0]
	v_pk_mul_f32 v[32:33], v[32:33], v[38:39] op_sel_hi:[1,0]
	v_pk_mul_f32 v[30:31], v[30:31], v[38:39] op_sel_hi:[1,0]
	v_pk_mul_f32 v[28:29], v[28:29], v[38:39] op_sel_hi:[1,0]
	v_mov_b64_e32 v[144:145], v[190:191]
	s_branch .LBB0_448

; __device__ __forceinline__ void kv_lwrite(const KVRegs& r, char* lds, int buf) {
;   const int tid = TIDX, row = tid >> 3, cq = tid & 7;
; template <int MODE>
; __device__ __forceinline__ void nsa_compute(int cur, int buf, int t, int hl, u64 mymask, const bf16x8 (&Qf)[2][2], f32x4 (&O)[4][2], float (&m)[2], float (&l)[2],
;                                             const float (&inv)[2], float* impw, char* lds) {
;     ...
;         const float mxa = fmaxf(fmaxf(sv[0][0], sv[0][1]), sv[0][2]), mxb = fmaxf(fmaxf(sv[0][3], sv[1][0]), sv[1][1]);
;         float mx = fmaxf(fmaxf(fmaxf(sv[1][2], sv[1][3]), mxa), mxb);
;         if (MODE == 2) mx = selok ? mx : -__builtin_inff();
;         if (__any(mx > m[r] + 8.0f)) {
;           mx = fmaxf(mx, __shfl_xor(mx, 16)); mx = fmaxf(mx, __shfl_xor(mx, 32));
;           const float mn = fmaxf(m[r], mx), al = __builtin_amdgcn_exp2f(m[r] - mn);
;           m[r] = mn; l[r] *= al;
;           if (MODE != 0) {
; #pragma unroll
;             for (int df = 0; df < 4; ++df) O[df][r] *= al;
;           }
;         }
;         const float me = (MODE == 2) ? (selok ? m[r] : __builtin_inff()) : m[r];
;         float ps = 0.f;
; #pragma unroll
;         for (int kk = 0; kk < 2; ++kk)
; #pragma unroll
;           for (int e = 0; e < 4; ++e) { pv[kk][e] = __builtin_amdgcn_exp2f(sv[kk][e] - me); ps += pv[kk][e]; }
;         l[r] += ps;
;       }
;       if (MODE != 0) {
;         const unsigned w0 = pk2(pv[0][0], pv[0][1]), w1 = pk2(pv[0][2], pv[0][3]), w2 = pk2(pv[1][0], pv[1][1]), w3 = pk2(pv[1][2], pv[1][3]);
;         u32x4 pw; pw.x = w0; pw.y = w1; pw.z = w2; pw.w = w3;
;         Pf[r] = __builtin_bit_cast(bf16x8, pw);
;       }
;     }
;     if (MODE != 0) {
;       bf16x8 vfr[4];
; #pragma unroll
;       for (int df = 0; df < 4; ++df) {
;         const bf16x4 va = *(const bf16x4*)(vt + (df * 16 + fr) * 68 + 32 * s2 + 4 * fq);
;         const bf16x4 vb = *(const bf16x4*)(vt + (df * 16 + fr) * 68 + 32 * s2 + 16 + 4 * fq);
;         bf16x8 vf; vf[0] = va[0]; vf[1] = va[1]; vf[2] = va[2]; vf[3] = va[3]; vf[4] = vb[0]; vf[5] = vb[1]; vf[6] = vb[2]; vf[7] = vb[3];
;         vfr[df] = vf;
;       }
;       __builtin_amdgcn_s_setprio(1);
; #pragma unroll
;       for (int df = 0; df < 4; ++df)
; #pragma unroll
;         for (int r = 0; r < 2; ++r) O[df][r] = mfma16(vfr[df], Pf[r], O[df][r]);
;       __builtin_amdgcn_s_setprio(0);
;     }
.LBB0_461:
.LBB0_462:
	v_cndmask_b32_e64 v129, v188, v228, s[36:37]
	v_sub_f32_e32 v115, v127, v129
	v_exp_f32_e32 v115, v115
	v_sub_f32_e32 v116, v116, v129
	v_exp_f32_e32 v116, v116
	v_sub_f32_e32 v117, v117, v129
	v_exp_f32_e32 v117, v117
	v_sub_f32_e32 v114, v114, v129
	v_exp_f32_e32 v114, v114
	v_add_f32_e32 v119, v116, v115
	v_add_f32_e32 v119, v117, v119
	v_sub_f32_e32 v113, v113, v129
	v_add_f32_e32 v120, v114, v119
	v_exp_f32_e32 v119, v113
	v_sub_f32_e32 v112, v112, v129
	v_add_f32_e32 v113, v119, v120
	v_exp_f32_e32 v120, v112
	s_nop 0
	v_add_f32_e32 v112, v120, v113
	v_sub_f32_e32 v113, v128, v129
	v_exp_f32_e32 v121, v113
	v_sub_f32_e32 v113, v118, v129
	v_exp_f32_e32 v118, v113
	v_add_f32_e32 v112, v121, v112
	v_add_f32_e32 v112, v118, v112
	v_add_f32_e32 v146, v146, v112
	s_waitcnt lgkmcnt(3)
	v_fmamk_f32 v113, v108, 0x3e38aa3b, v171
	v_fmamk_f32 v112, v109, 0x3e38aa3b, v170
	s_waitcnt lgkmcnt(2)
	v_fmamk_f32 v109, v110, 0x3e38aa3b, v173
	v_fmamk_f32 v108, v111, 0x3e38aa3b, v172
	s_waitcnt lgkmcnt(1)
	v_fmamk_f32 v111, v104, 0x3e38aa3b, v175
	v_fmamk_f32 v110, v105, 0x3e38aa3b, v174
	s_waitcnt lgkmcnt(0)
	v_fmamk_f32 v105, v106, 0x3e38aa3b, v193
	v_fmamk_f32 v104, v107, 0x3e38aa3b, v192
	v_max3_f32 v106, v113, v112, v109
	v_max3_f32 v107, v108, v111, v110
	v_max_f32_e32 v122, v105, v104
	v_max3_f32 v106, v122, v106, v107
	v_cndmask_b32_e64 v106, v106, v225, s[36:37]
	v_add_f32_e32 v107, 0x41000000, v189
	v_cmp_gt_f32_e32 vcc, v106, v107
	s_cbranch_vccz .LBB0_464
	ds_bpermute_b32 v107, v233, v106
	v_max_f32_e32 v106, v106, v106
	s_waitcnt lgkmcnt(0)
	v_max_f32_e32 v107, v107, v107
	v_max_f32_e32 v106, v106, v107
	ds_bpermute_b32 v107, v234, v106
	s_waitcnt lgkmcnt(0)
	v_max3_f32 v106, v189, v106, v107
	v_sub_f32_e32 v107, v189, v106
	v_exp_f32_e32 v122, v107
	v_mov_b32_e32 v189, v106
	v_mul_f32_e32 v147, v147, v122
	v_pk_mul_f32 v[46:47], v[46:47], v[122:123] op_sel_hi:[1,0]
	v_pk_mul_f32 v[44:45], v[44:45], v[122:123] op_sel_hi:[1,0]
	v_pk_mul_f32 v[42:43], v[42:43], v[122:123] op_sel_hi:[1,0]
	v_pk_mul_f32 v[40:41], v[40:41], v[122:123] op_sel_hi:[1,0]
	v_pk_mul_f32 v[38:39], v[38:39], v[122:123] op_sel_hi:[1,0]
	v_pk_mul_f32 v[36:37], v[36:37], v[122:123] op_sel_hi:[1,0]
	v_pk_mul_f32 v[34:35], v[34:35], v[122:123] op_sel_hi:[1,0]
	v_pk_mul_f32 v[32:33], v[32:33], v[122:123] op_sel_hi:[1,0]
	s_branch .LBB0_465
.LBB0_464:
.LBB0_465:
	v_cndmask_b32_e64 v106, v189, v228, s[36:37]
	v_sub_f32_e32 v107, v113, v106
	v_exp_f32_e32 v136, v107
	v_sub_f32_e32 v107, v112, v106
	v_exp_f32_e32 v137, v107
	v_sub_f32_e32 v107, v109, v106
	v_exp_f32_e32 v138, v107
	v_sub_f32_e32 v107, v108, v106
	v_exp_f32_e32 v139, v107
	v_sub_f32_e32 v107, v111, v106
	v_cvt_pk_bf16_f32 v132, v115, v116
	v_cvt_pk_bf16_f32 v133, v117, v114
	v_cvt_pk_bf16_f32 v134, v119, v120
	v_cvt_pk_bf16_f32 v135, v121, v118
	v_exp_f32_e32 v140, v107
	v_sub_f32_e32 v107, v110, v106
	ds_read2_b64 v[108:111], v123 offset0:8 offset1:12
	ds_read2_b64 v[112:115], v124 offset0:24 offset1:28
	ds_read2_b64 v[116:119], v125 offset0:40 offset1:44
	ds_read2_b64 v[120:123], v126 offset0:56 offset1:60
	v_sub_f32_e32 v105, v105, v106
	v_sub_f32_e32 v104, v104, v106
	v_exp_f32_e32 v141, v107
	v_exp_f32_e32 v142, v105
	v_exp_f32_e32 v143, v104
	v_cvt_pk_bf16_f32 v148, v136, v137
	v_cvt_pk_bf16_f32 v149, v138, v139
	v_cvt_pk_bf16_f32 v150, v140, v141
	v_cvt_pk_bf16_f32 v151, v142, v143
	s_setprio 1
	s_waitcnt lgkmcnt(3)
	v_mfma_f32_16x16x32_bf16 v[104:107], v[108:111], v[132:135], v[28:31]
	v_mfma_f32_16x16x32_bf16 v[108:111], v[108:111], v[148:151], v[44:47]
	s_waitcnt lgkmcnt(2)
	v_mfma_f32_16x16x32_bf16 v[124:127], v[112:115], v[132:135], v[24:27]
	v_mfma_f32_16x16x32_bf16 v[112:115], v[112:115], v[148:151], v[40:43]
	s_waitcnt lgkmcnt(1)
	v_mfma_f32_16x16x32_bf16 v[128:131], v[116:119], v[132:135], v[20:23]
	v_mfma_f32_16x16x32_bf16 v[116:119], v[116:119], v[148:151], v[36:39]
	s_waitcnt lgkmcnt(0)
	v_mfma_f32_16x16x32_bf16 v[132:135], v[120:123], v[132:135], v[16:19]
	v_mfma_f32_16x16x32_bf16 v[120:123], v[120:123], v[148:151], v[32:35]
	s_setprio 0
	s_cmp_lt_i32 s62, 0
	s_cbranch_scc1 .LBB0_467
	v_mov_b32 v16, v179
	s_nop 0
	v_ashrrev_i32_e32 v17, 3, v16
	v_xor_b32_e32 v19, v17, v16
	v_lshlrev_b32_e32 v16, 3, v16
	v_lshlrev_b32_e32 v19, 4, v19
	v_and_b32_e32 v16, 56, v16
	v_lshlrev_b32_e32 v18, 7, v17
	v_and_b32_e32 v19, 0x70, v19
	v_mul_u32_u24_e32 v16, 0x88, v16
	v_lshlrev_b32_e32 v17, 1, v17
	v_add3_u32 v18, s63, v18, v19
	v_add3_u32 v16, s71, v16, v17
	s_waitcnt vmcnt(1)
	ds_write_b128 v18, v[64:67]
	s_waitcnt vmcnt(0)
	ds_write_b16 v16, v68 offset:16384
	ds_write_b16_d16_hi v16, v68 offset:16520
	ds_write_b16 v16, v69 offset:16656
	ds_write_b16_d16_hi v16, v69 offset:16792
	ds_write_b16 v16, v70 offset:16928
	ds_write_b16_d16_hi v16, v70 offset:17064
	ds_write_b16 v16, v71 offset:17200
	ds_write_b16_d16_hi v16, v71 offset:17336

; __device__ __forceinline__ void kv_lwrite(const KVRegs& r, char* lds, int buf) {
;   const int tid = TIDX, row = tid >> 3, cq = tid & 7;
; template <int MODE>
; __device__ __forceinline__ void nsa_compute(int cur, int buf, int t, int hl, u64 mymask, const bf16x8 (&Qf)[2][2], f32x4 (&O)[4][2], float (&m)[2], float (&l)[2],
;                                             const float (&inv)[2], float* impw, char* lds) {
;     ...
;         const float mxa = fmaxf(fmaxf(sv[0][0], sv[0][1]), sv[0][2]), mxb = fmaxf(fmaxf(sv[0][3], sv[1][0]), sv[1][1]);
;         float mx = fmaxf(fmaxf(fmaxf(sv[1][2], sv[1][3]), mxa), mxb);
;         if (MODE == 2) mx = selok ? mx : -__builtin_inff();
;         if (__any(mx > m[r] + 8.0f)) {
;           mx = fmaxf(mx, __shfl_xor(mx, 16)); mx = fmaxf(mx, __shfl_xor(mx, 32));
;           const float mn = fmaxf(m[r], mx), al = __builtin_amdgcn_exp2f(m[r] - mn);
;           m[r] = mn; l[r] *= al;
;           if (MODE != 0) {
; #pragma unroll
;             for (int df = 0; df < 4; ++df) O[df][r] *= al;
;           }
;         }
;         const float me = (MODE == 2) ? (selok ? m[r] : __builtin_inff()) : m[r];
;         float ps = 0.f;
; #pragma unroll
;         for (int kk = 0; kk < 2; ++kk)
; #pragma unroll
;           for (int e = 0; e < 4; ++e) { pv[kk][e] = __builtin_amdgcn_exp2f(sv[kk][e] - me); ps += pv[kk][e]; }
;         l[r] += ps;
;       }
;       if (MODE != 0) {
;         const unsigned w0 = pk2(pv[0][0], pv[0][1]), w1 = pk2(pv[0][2], pv[0][3]), w2 = pk2(pv[1][0], pv[1][1]), w3 = pk2(pv[1][2], pv[1][3]);
;         u32x4 pw; pw.x = w0; pw.y = w1; pw.z = w2; pw.w = w3;
;         Pf[r] = __builtin_bit_cast(bf16x8, pw);
;       }
;     }
;     if (MODE != 0) {
;       bf16x8 vfr[4];
; #pragma unroll
;       for (int df = 0; df < 4; ++df) {
;         const bf16x4 va = *(const bf16x4*)(vt + (df * 16 + fr) * 68 + 32 * s2 + 4 * fq);
;         const bf16x4 vb = *(const bf16x4*)(vt + (df * 16 + fr) * 68 + 32 * s2 + 16 + 4 * fq);
;         bf16x8 vf; vf[0] = va[0]; vf[1] = va[1]; vf[2] = va[2]; vf[3] = va[3]; vf[4] = vb[0]; vf[5] = vb[1]; vf[6] = vb[2]; vf[7] = vb[3];
;         vfr[df] = vf;
;       }
;       __builtin_amdgcn_s_setprio(1);
; #pragma unroll
;       for (int df = 0; df < 4; ++df)
; #pragma unroll
;         for (int r = 0; r < 2; ++r) O[df][r] = mfma16(vfr[df], Pf[r], O[df][r]);
;       __builtin_amdgcn_s_setprio(0);
;     }
.LBB0_478:
.LBB0_479:
	v_cndmask_b32_e64 v165, v188, v228, s[36:37]
	v_sub_f32_e32 v151, v163, v165
	v_exp_f32_e32 v151, v151
	v_sub_f32_e32 v152, v152, v165
	v_exp_f32_e32 v152, v152
	v_sub_f32_e32 v153, v153, v165
	v_exp_f32_e32 v153, v153
	v_sub_f32_e32 v150, v150, v165
	v_exp_f32_e32 v150, v150
	v_add_f32_e32 v155, v152, v151
	v_add_f32_e32 v155, v153, v155
	v_sub_f32_e32 v149, v149, v165
	v_add_f32_e32 v156, v150, v155
	v_exp_f32_e32 v155, v149
	v_sub_f32_e32 v148, v148, v165
	v_add_f32_e32 v149, v155, v156
	v_exp_f32_e32 v156, v148
	s_nop 0
	v_add_f32_e32 v148, v156, v149
	v_sub_f32_e32 v149, v164, v165
	v_exp_f32_e32 v157, v149
	v_sub_f32_e32 v149, v154, v165
	v_exp_f32_e32 v154, v149
	v_add_f32_e32 v148, v157, v148
	v_add_f32_e32 v148, v154, v148
	v_add_f32_e32 v190, v190, v148
	s_waitcnt lgkmcnt(3)
	v_fmamk_f32 v149, v140, 0x3e38aa3b, v203
	v_fmamk_f32 v148, v141, 0x3e38aa3b, v202
	s_waitcnt lgkmcnt(2)
	v_fmamk_f32 v141, v142, 0x3e38aa3b, v205
	v_fmamk_f32 v140, v143, 0x3e38aa3b, v204
	s_waitcnt lgkmcnt(1)
	v_fmamk_f32 v143, v136, 0x3e38aa3b, v207
	v_fmamk_f32 v142, v137, 0x3e38aa3b, v206
	s_waitcnt lgkmcnt(0)
	v_fmamk_f32 v158, v138, 0x3e38aa3b, v209
	v_fmamk_f32 v136, v139, 0x3e38aa3b, v208
	v_max3_f32 v137, v149, v148, v141
	v_max3_f32 v138, v140, v143, v142
	v_max_f32_e32 v139, v158, v136
	v_max3_f32 v137, v139, v137, v138
	v_cndmask_b32_e64 v137, v137, v225, s[36:37]
	v_add_f32_e32 v138, 0x41000000, v189
	v_cmp_gt_f32_e32 vcc, v137, v138
	s_cbranch_vccz .LBB0_481
	ds_bpermute_b32 v138, v233, v137
	v_max_f32_e32 v137, v137, v137
	s_waitcnt lgkmcnt(0)
	v_max_f32_e32 v138, v138, v138
	v_max_f32_e32 v137, v137, v138
	ds_bpermute_b32 v138, v234, v137
	s_waitcnt lgkmcnt(0)
	v_max3_f32 v137, v189, v137, v138
	v_sub_f32_e32 v138, v189, v137
	v_exp_f32_e32 v138, v138
	v_mov_b32_e32 v189, v137
	v_mul_f32_e32 v191, v191, v138
	v_pk_mul_f32 v[22:23], v[22:23], v[138:139] op_sel_hi:[1,0]
	v_pk_mul_f32 v[20:21], v[20:21], v[138:139] op_sel_hi:[1,0]
	v_pk_mul_f32 v[30:31], v[30:31], v[138:139] op_sel_hi:[1,0]
	v_pk_mul_f32 v[28:29], v[28:29], v[138:139] op_sel_hi:[1,0]
	v_pk_mul_f32 v[38:39], v[38:39], v[138:139] op_sel_hi:[1,0]
	v_pk_mul_f32 v[36:37], v[36:37], v[138:139] op_sel_hi:[1,0]
	v_pk_mul_f32 v[46:47], v[46:47], v[138:139] op_sel_hi:[1,0]
	v_pk_mul_f32 v[44:45], v[44:45], v[138:139] op_sel_hi:[1,0]
	s_branch .LBB0_482
.LBB0_481:
.LBB0_482:
	v_cndmask_b32_e64 v163, v189, v228, s[36:37]
	v_cvt_pk_bf16_f32 v164, v151, v152
	v_cvt_pk_bf16_f32 v165, v153, v150
	v_cvt_pk_bf16_f32 v166, v155, v156
	v_cvt_pk_bf16_f32 v167, v157, v154
	v_sub_f32_e32 v137, v149, v163
	v_sub_f32_e32 v138, v148, v163
	v_sub_f32_e32 v139, v141, v163
	v_sub_f32_e32 v140, v140, v163
	v_sub_f32_e32 v141, v143, v163
	v_sub_f32_e32 v142, v142, v163
	v_sub_f32_e32 v143, v158, v163
	v_sub_f32_e32 v136, v136, v163
	ds_read2_b64 v[148:151], v159 offset0:8 offset1:12
	ds_read2_b64 v[152:155], v160 offset0:24 offset1:28
	ds_read2_b64 v[156:159], v161 offset0:40 offset1:44
	ds_read2_b64 v[160:163], v162 offset0:56 offset1:60
	v_exp_f32_e32 v137, v137
	v_exp_f32_e32 v138, v138
	v_exp_f32_e32 v139, v139
	v_exp_f32_e32 v140, v140
	v_exp_f32_e32 v141, v141
	v_exp_f32_e32 v142, v142
	v_exp_f32_e32 v143, v143
	v_exp_f32_e32 v136, v136
	v_cvt_pk_bf16_f32 v168, v137, v138
	v_cvt_pk_bf16_f32 v169, v139, v140
	v_cvt_pk_bf16_f32 v170, v141, v142
	v_cvt_pk_bf16_f32 v171, v143, v136
	s_setprio 1
	s_waitcnt lgkmcnt(3)
	v_mfma_f32_16x16x32_bf16 v[16:19], v[148:151], v[164:167], v[16:19]
	v_mfma_f32_16x16x32_bf16 v[20:23], v[148:151], v[168:171], v[20:23]
	s_waitcnt lgkmcnt(2)
	v_mfma_f32_16x16x32_bf16 v[24:27], v[152:155], v[164:167], v[24:27]
	v_mfma_f32_16x16x32_bf16 v[28:31], v[152:155], v[168:171], v[28:31]
	s_waitcnt lgkmcnt(1)
	v_mfma_f32_16x16x32_bf16 v[32:35], v[156:159], v[164:167], v[32:35]
	v_mfma_f32_16x16x32_bf16 v[36:39], v[156:159], v[168:171], v[36:39]
	s_waitcnt lgkmcnt(0)
	v_mfma_f32_16x16x32_bf16 v[40:43], v[160:163], v[164:167], v[40:43]
	v_mfma_f32_16x16x32_bf16 v[44:47], v[160:163], v[168:171], v[44:47]
	s_setprio 0
	s_cmp_lt_i32 s75, 0
	s_cbranch_scc1 .LBB0_484
	v_mov_b32 v148, v179
	s_nop 0
	v_ashrrev_i32_e32 v149, 3, v148
	v_xor_b32_e32 v151, v149, v148
	v_lshlrev_b32_e32 v148, 3, v148
	v_lshlrev_b32_e32 v151, 4, v151
	v_and_b32_e32 v148, 56, v148
	v_lshlrev_b32_e32 v150, 7, v149
	v_and_b32_e32 v151, 0x70, v151
	v_mul_u32_u24_e32 v148, 0x88, v148
	v_lshlrev_b32_e32 v149, 1, v149
	v_add3_u32 v150, s72, v150, v151
	v_add3_u32 v148, s73, v148, v149
	s_waitcnt vmcnt(1)
	ds_write_b128 v150, v[48:51]
	s_waitcnt vmcnt(0)
	ds_write_b16 v148, v52 offset:16384
	ds_write_b16_d16_hi v148, v52 offset:16520
	ds_write_b16 v148, v53 offset:16656
	ds_write_b16_d16_hi v148, v53 offset:16792
	ds_write_b16 v148, v54 offset:16928
	ds_write_b16_d16_hi v148, v54 offset:17064
	ds_write_b16 v148, v55 offset:17200
	ds_write_b16_d16_hi v148, v55 offset:17336
